# v54 + LN1 phase: y1 rows prefetched two 8-row steps ahead (second register set rotated by v_mov, vmcnt(0) at the rotation point) instead of one
# speedup vs baseline: 1.0011x; 1.0011x over previous
; __device__ __forceinline__ size_t ytile(int row, int col) { return ((((size_t)(row >> 8) * 16) + (col >> 8)) * 256 + (row & 255)) * 256 + (col & 255); }
; template <bool LN1>
; __device__ __forceinline__ void ln_phase(Frame& F, const bf16_t* Yin, const float* ga, const float* be, const float* modf, float* stats, bf16_t* ob16, float* of32) {
;     ...
;     for (int rb = F.vcu * 64; rb < T; rb += F.G * 64) {
;         const int b = rb / S;
;         f32x4 ca[2], cb[2];
; #pragma unroll
;         for (int n = 0; n < 2; ++n) {
;             if (LN1) { const f32x4 sc1 = *(const f32x4*)(modf + (size_t)b * NADA + 4 * D + c0 + 4 * n) + 1.0f, sh = *(const f32x4*)(modf + (size_t)b * NADA + 3 * D + c0 + 4 * n);
;                 ca[n] = *(const f32x4*)(ga + c0 + 4 * n) * sc1; cb[n] = *(const f32x4*)(be + c0 + 4 * n) * sc1 + sh; }
;             else { ca[n] = *(const f32x4*)(ga + c0 + 4 * n); cb[n] = *(const f32x4*)(be + c0 + 4 * n); }
;         }
;         u32x4 nx[8];
; #pragma unroll
;         for (int k = 0; k < 8; ++k) nx[k] = *(const u32x4*)(Yin + ytile(rb + k, c0));
.LBB0_1104:
	s_ashr_i32 s0, s6, 31
	s_lshr_b32 s0, s0, 20
	s_add_i32 s0, s6, s0
	s_ashr_i32 s0, s0, 12
	s_mul_hi_i32 s1, s0, 0x18000
	s_mul_i32 s0, s0, 0x18000
	s_add_u32 s0, s20, s0
	s_addc_u32 s1, s21, s1
	s_waitcnt vmcnt(0)
	v_lshl_add_u64 v[2:3], v[34:35], 2, s[0:1]
	v_add_co_u32_e32 v8, vcc, s23, v2
	s_ashr_i32 s0, s6, 8
	s_nop 0
	v_addc_co_u32_e32 v9, vcc, 0, v3, vcc
	s_ashr_i32 s1, s0, 31
	v_lshl_add_u64 v[4:5], v[2:3], 0, s[14:15]
	v_lshl_add_u64 v[6:7], v[2:3], 0, s[16:17]
	v_add_co_u32_e32 v2, vcc, s24, v2
	s_lshl_b64 s[18:19], s[0:1], 12
	s_nop 0
	v_addc_co_u32_e32 v3, vcc, 0, v3, vcc
	v_lshl_add_u64 v[26:27], s[18:19], 0, v[40:41]
	s_and_b32 s18, s6, 0xc0
	global_load_dwordx4 v[50:53], v[8:9], off
	global_load_dwordx4 v[64:67], v[2:3], off
	global_load_dwordx4 v[54:57], v[4:5], off offset:16
	global_load_dwordx4 v[58:61], v[6:7], off offset:16
	global_load_dwordx4 v[68:71], v[36:37], off offset:16
	global_load_dwordx4 v[72:75], v[36:37], off
	global_load_dwordx4 v[76:79], v[38:39], off offset:16
	global_load_dwordx4 v[80:83], v[38:39], off
	v_or_b32_e32 v2, s18, v26
	v_mov_b32_e32 v3, v27
	v_or3_b32 v4, s18, 1, v26
	v_mov_b32_e32 v5, v27
	v_or3_b32 v10, s18, 2, v26
	v_mov_b32_e32 v11, v27
	v_or3_b32 v12, s18, 3, v26
	v_mov_b32_e32 v13, v27
	v_or3_b32 v18, s18, 4, v26
	v_mov_b32_e32 v19, v27
	v_or3_b32 v20, s18, 5, v26
	v_mov_b32_e32 v21, v27
	v_or3_b32 v28, s18, 6, v26
	v_mov_b32_e32 v29, v27
	v_or3_b32 v26, s18, 7, v26
	v_lshlrev_b64 v[2:3], 9, v[2:3]
	v_lshlrev_b64 v[4:5], 9, v[4:5]
	v_lshlrev_b64 v[10:11], 9, v[10:11]
	v_lshlrev_b64 v[12:13], 9, v[12:13]
	v_lshlrev_b64 v[18:19], 9, v[18:19]
	v_lshlrev_b64 v[20:21], 9, v[20:21]
	v_lshlrev_b64 v[28:29], 9, v[28:29]
	v_lshlrev_b64 v[26:27], 9, v[26:27]
	v_lshl_add_u64 v[2:3], v[42:43], 0, v[2:3]
	v_lshl_add_u64 v[6:7], v[42:43], 0, v[4:5]
	v_lshl_add_u64 v[10:11], v[42:43], 0, v[10:11]
	v_lshl_add_u64 v[14:15], v[42:43], 0, v[12:13]
	v_lshl_add_u64 v[18:19], v[42:43], 0, v[18:19]
	v_lshl_add_u64 v[22:23], v[42:43], 0, v[20:21]
	v_lshl_add_u64 v[28:29], v[42:43], 0, v[28:29]
	v_lshl_add_u64 v[30:31], v[42:43], 0, v[26:27]
	global_load_dwordx4 v[2:5], v[2:3], off
	s_nop 0
	global_load_dwordx4 v[6:9], v[6:7], off
	s_nop 0
	global_load_dwordx4 v[10:13], v[10:11], off
	s_nop 0
	global_load_dwordx4 v[14:17], v[14:15], off
	s_nop 0
	global_load_dwordx4 v[18:21], v[18:19], off
	s_nop 0
	global_load_dwordx4 v[22:25], v[22:23], off
	s_nop 0
	global_load_dwordx4 v[26:29], v[28:29], off
	s_nop 0
	global_load_dwordx4 v[30:33], v[30:31], off
	s_lshl_b64 s[34:35], s[0:1], 12
	v_lshl_add_u64 v[242:243], s[34:35], 0, v[40:41]
	s_or_b32 s34, s18, 8
	v_or_b32_e32 v254, s34, v242
	v_mov_b32_e32 v255, v243
	v_lshlrev_b64 v[254:255], 9, v[254:255]
	v_lshl_add_u64 v[254:255], v[42:43], 0, v[254:255]
	global_load_dwordx4 v[218:221], v[254:255], off
	v_or3_b32 v254, s34, 1, v242
	v_mov_b32_e32 v255, v243
	v_lshlrev_b64 v[254:255], 9, v[254:255]
	v_lshl_add_u64 v[254:255], v[42:43], 0, v[254:255]
	global_load_dwordx4 v[222:225], v[254:255], off
	v_or3_b32 v254, s34, 2, v242
	v_mov_b32_e32 v255, v243
	v_lshlrev_b64 v[254:255], 9, v[254:255]
	v_lshl_add_u64 v[254:255], v[42:43], 0, v[254:255]
	global_load_dwordx4 v[226:229], v[254:255], off
	v_or3_b32 v254, s34, 3, v242
	v_mov_b32_e32 v255, v243
	v_lshlrev_b64 v[254:255], 9, v[254:255]
	v_lshl_add_u64 v[254:255], v[42:43], 0, v[254:255]
	global_load_dwordx4 v[230:233], v[254:255], off
	v_or3_b32 v254, s34, 4, v242
	v_mov_b32_e32 v255, v243
	v_lshlrev_b64 v[254:255], 9, v[254:255]
	v_lshl_add_u64 v[254:255], v[42:43], 0, v[254:255]
	global_load_dwordx4 v[234:237], v[254:255], off
	v_or3_b32 v254, s34, 5, v242
	v_mov_b32_e32 v255, v243
	v_lshlrev_b64 v[254:255], 9, v[254:255]
	v_lshl_add_u64 v[254:255], v[42:43], 0, v[254:255]
	global_load_dwordx4 v[238:241], v[254:255], off
	v_or3_b32 v254, s34, 6, v242
	v_mov_b32_e32 v255, v243
	v_lshlrev_b64 v[254:255], 9, v[254:255]
	v_lshl_add_u64 v[254:255], v[42:43], 0, v[254:255]
	global_load_dwordx4 v[246:249], v[254:255], off
	v_or3_b32 v254, s34, 7, v242
	v_mov_b32_e32 v255, v243
	v_lshlrev_b64 v[254:255], 9, v[254:255]
	v_lshl_add_u64 v[254:255], v[42:43], 0, v[254:255]
	global_load_dwordx4 v[250:253], v[254:255], off
	s_lshl_b64 s[0:1], s[0:1], 14
	v_lshl_add_u64 v[48:49], s[0:1], 0, v[44:45]
	s_mov_b64 s[18:19], 0
	s_mov_b32 s28, s11
	s_waitcnt vmcnt(0)
	v_pk_add_f32 v[84:85], v[52:53], 1.0 op_sel_hi:[1,0]
	v_pk_add_f32 v[86:87], v[50:51], 1.0 op_sel_hi:[1,0]
	v_pk_add_f32 v[56:57], v[56:57], 1.0 op_sel_hi:[1,0]
	v_pk_add_f32 v[62:63], v[54:55], 1.0 op_sel_hi:[1,0]
	v_pk_mul_f32 v[50:51], v[56:57], v[70:71]
	v_pk_mul_f32 v[52:53], v[62:63], v[68:69]
	v_pk_fma_f32 v[54:55], v[56:57], v[78:79], v[60:61]
	v_pk_fma_f32 v[56:57], v[62:63], v[76:77], v[58:59]
	v_pk_mul_f32 v[58:59], v[84:85], v[74:75]
	v_pk_mul_f32 v[60:61], v[86:87], v[72:73]
	v_pk_fma_f32 v[62:63], v[84:85], v[82:83], v[66:67]
	v_pk_fma_f32 v[64:65], v[86:87], v[80:81], v[64:65]
	s_branch .LBB0_1106

; template <bool LN1>
; __device__ __forceinline__ void ln_phase(Frame& F, const bf16_t* Yin, const float* ga, const float* be, const float* modf, float* stats, bf16_t* ob16, float* of32) {
;     ...
; #pragma unroll
;             for (int k = 0; k < 8; ++k) { pg8::unpack8(nx[k], v[k][0], v[k][1]);
;                 float s = ((v[k][0][0] + v[k][0][1]) + (v[k][0][2] + v[k][0][3])) + ((v[k][1][0] + v[k][1][1]) + (v[k][1][2] + v[k][1][3]));
;                 float q = ((v[k][0][0] * v[k][0][0] + v[k][0][1] * v[k][0][1]) + (v[k][0][2] * v[k][0][2] + v[k][0][3] * v[k][0][3])) + ((v[k][1][0] * v[k][1][0] + v[k][1][1] * v[k][1][1]) + (v[k][1][2] * v[k][1][2] + v[k][1][3] * v[k][1][3]));
;                 s = wave_sum(s); q = wave_sum(q);
;                 if (lane == 0) rd[k * 8 + w] = (f32x2){s, q}; }
.LBB0_1106:
	v_lshlrev_b32_e32 v188, 16, v2
	v_and_b32_e32 v190, 0xffff0000, v2
	v_lshlrev_b32_e32 v192, 16, v3
	v_and_b32_e32 v194, 0xffff0000, v3
	v_lshlrev_b32_e32 v178, 16, v4
	v_and_b32_e32 v180, 0xffff0000, v4
	v_lshlrev_b32_e32 v182, 16, v5
	v_and_b32_e32 v184, 0xffff0000, v5
	v_mul_f32_e32 v189, v188, v188
	v_mul_f32_e32 v191, v190, v190
	v_mul_f32_e32 v193, v192, v192
	v_mul_f32_e32 v195, v194, v194
	v_mul_f32_e32 v179, v178, v178
	v_mul_f32_e32 v181, v180, v180
	v_mul_f32_e32 v183, v182, v182
	v_mul_f32_e32 v185, v184, v184
	v_pk_add_f32 v[66:67], v[188:189], v[190:191]
	v_pk_add_f32 v[68:69], v[192:193], v[194:195]
	v_pk_add_f32 v[70:71], v[182:183], v[184:185]
	v_pk_add_f32 v[66:67], v[66:67], v[68:69]
	v_pk_add_f32 v[68:69], v[178:179], v[180:181]
	s_and_b32 s0, s18, 64
	v_pk_add_f32 v[68:69], v[68:69], v[70:71]
	s_lshl_b32 s0, s0, 3
	v_pk_add_f32 v[66:67], v[66:67], v[68:69]
	ds_bpermute_b32 v68, v1, v66
	ds_bpermute_b32 v69, v1, v67
	s_add_i32 s29, s0, 0
	s_add_i32 s33, s29, s25
	s_waitcnt lgkmcnt(0)
	v_pk_add_f32 v[66:67], v[66:67], v[68:69]
	ds_bpermute_b32 v68, v187, v66
	ds_bpermute_b32 v69, v187, v67
	s_waitcnt lgkmcnt(0)
	v_pk_add_f32 v[66:67], v[66:67], v[68:69]
	ds_bpermute_b32 v68, v200, v66
	ds_bpermute_b32 v69, v200, v67
	s_waitcnt lgkmcnt(0)
	v_pk_add_f32 v[66:67], v[66:67], v[68:69]
	ds_bpermute_b32 v68, v201, v66
	ds_bpermute_b32 v69, v201, v67
	s_waitcnt lgkmcnt(0)
	v_pk_add_f32 v[66:67], v[66:67], v[68:69]
	ds_bpermute_b32 v68, v202, v66
	ds_bpermute_b32 v69, v202, v67
	s_waitcnt lgkmcnt(0)
	v_pk_add_f32 v[66:67], v[66:67], v[68:69]
	ds_bpermute_b32 v68, v203, v66
	ds_bpermute_b32 v69, v203, v67
	s_and_saveexec_b64 s[0:1], s[2:3]
	s_cbranch_execz .LBB0_1108
	s_waitcnt lgkmcnt(0)
	v_pk_add_f32 v[66:67], v[66:67], v[68:69]
	v_mov_b32_e32 v68, s33
	ds_write_b64 v68, v[66:67]
.LBB0_1108:
	s_or_b64 exec, exec, s[0:1]
	v_lshlrev_b32_e32 v170, 16, v6
	v_and_b32_e32 v172, 0xffff0000, v6
	v_lshlrev_b32_e32 v174, 16, v7
	v_and_b32_e32 v176, 0xffff0000, v7
	v_lshlrev_b32_e32 v162, 16, v8
	v_and_b32_e32 v164, 0xffff0000, v8
	v_lshlrev_b32_e32 v166, 16, v9
	v_and_b32_e32 v168, 0xffff0000, v9
	v_mul_f32_e32 v171, v170, v170
	v_mul_f32_e32 v173, v172, v172
	v_mul_f32_e32 v175, v174, v174
	v_mul_f32_e32 v177, v176, v176
	v_mul_f32_e32 v163, v162, v162
	v_mul_f32_e32 v165, v164, v164
	v_mul_f32_e32 v167, v166, v166
	v_mul_f32_e32 v169, v168, v168
	v_pk_add_f32 v[66:67], v[170:171], v[172:173]
	s_waitcnt lgkmcnt(0)
	v_pk_add_f32 v[68:69], v[174:175], v[176:177]
	v_pk_add_f32 v[70:71], v[166:167], v[168:169]
	v_pk_add_f32 v[66:67], v[66:67], v[68:69]
	v_pk_add_f32 v[68:69], v[162:163], v[164:165]
	s_nop 0
	v_pk_add_f32 v[68:69], v[68:69], v[70:71]
	s_nop 0
	v_pk_add_f32 v[66:67], v[66:67], v[68:69]
	ds_bpermute_b32 v68, v1, v66
	ds_bpermute_b32 v69, v1, v67
	s_waitcnt lgkmcnt(0)
	v_pk_add_f32 v[66:67], v[66:67], v[68:69]
	ds_bpermute_b32 v68, v187, v66
	ds_bpermute_b32 v69, v187, v67
	s_waitcnt lgkmcnt(0)
	v_pk_add_f32 v[66:67], v[66:67], v[68:69]
	ds_bpermute_b32 v68, v200, v66
	ds_bpermute_b32 v69, v200, v67
	s_waitcnt lgkmcnt(0)
	v_pk_add_f32 v[66:67], v[66:67], v[68:69]
	ds_bpermute_b32 v68, v201, v66
	ds_bpermute_b32 v69, v201, v67
	s_waitcnt lgkmcnt(0)
	v_pk_add_f32 v[66:67], v[66:67], v[68:69]
	ds_bpermute_b32 v68, v202, v66
	ds_bpermute_b32 v69, v202, v67
	s_waitcnt lgkmcnt(0)
	v_pk_add_f32 v[66:67], v[66:67], v[68:69]
	ds_bpermute_b32 v68, v203, v66
	ds_bpermute_b32 v69, v203, v67
	s_and_saveexec_b64 s[0:1], s[2:3]
	s_cbranch_execz .LBB0_1110
	s_waitcnt lgkmcnt(0)
	v_pk_add_f32 v[66:67], v[66:67], v[68:69]
	v_mov_b32_e32 v68, s33
	ds_write_b64 v68, v[66:67] offset:64
.LBB0_1110:
	s_or_b64 exec, exec, s[0:1]
	v_lshlrev_b32_e32 v154, 16, v10
	v_and_b32_e32 v156, 0xffff0000, v10
	v_lshlrev_b32_e32 v158, 16, v11
	v_and_b32_e32 v160, 0xffff0000, v11
	v_lshlrev_b32_e32 v146, 16, v12
	v_and_b32_e32 v148, 0xffff0000, v12
	v_lshlrev_b32_e32 v150, 16, v13
	v_and_b32_e32 v152, 0xffff0000, v13
	v_mul_f32_e32 v155, v154, v154
	v_mul_f32_e32 v157, v156, v156
	v_mul_f32_e32 v159, v158, v158
	v_mul_f32_e32 v161, v160, v160
	v_mul_f32_e32 v147, v146, v146
	v_mul_f32_e32 v149, v148, v148
	v_mul_f32_e32 v151, v150, v150
	v_mul_f32_e32 v153, v152, v152
	v_pk_add_f32 v[66:67], v[154:155], v[156:157]
	s_waitcnt lgkmcnt(0)
	v_pk_add_f32 v[68:69], v[158:159], v[160:161]
	v_pk_add_f32 v[70:71], v[150:151], v[152:153]
	v_pk_add_f32 v[66:67], v[66:67], v[68:69]
	v_pk_add_f32 v[68:69], v[146:147], v[148:149]
	s_nop 0
	v_pk_add_f32 v[68:69], v[68:69], v[70:71]
	s_nop 0
	v_pk_add_f32 v[66:67], v[66:67], v[68:69]
	ds_bpermute_b32 v68, v1, v66
	ds_bpermute_b32 v69, v1, v67
	s_waitcnt lgkmcnt(0)
	v_pk_add_f32 v[66:67], v[66:67], v[68:69]
	ds_bpermute_b32 v68, v187, v66
	ds_bpermute_b32 v69, v187, v67
	s_waitcnt lgkmcnt(0)
	v_pk_add_f32 v[66:67], v[66:67], v[68:69]
	ds_bpermute_b32 v68, v200, v66
	ds_bpermute_b32 v69, v200, v67
	s_waitcnt lgkmcnt(0)
	v_pk_add_f32 v[66:67], v[66:67], v[68:69]
	ds_bpermute_b32 v68, v201, v66
	ds_bpermute_b32 v69, v201, v67
	s_waitcnt lgkmcnt(0)
	v_pk_add_f32 v[66:67], v[66:67], v[68:69]
	ds_bpermute_b32 v68, v202, v66
	ds_bpermute_b32 v69, v202, v67
	s_waitcnt lgkmcnt(0)
	v_pk_add_f32 v[66:67], v[66:67], v[68:69]
	ds_bpermute_b32 v68, v203, v66
	ds_bpermute_b32 v69, v203, v67
	s_and_saveexec_b64 s[0:1], s[2:3]
	s_cbranch_execz .LBB0_1112
	s_waitcnt lgkmcnt(0)
	v_pk_add_f32 v[66:67], v[66:67], v[68:69]
	v_mov_b32_e32 v68, s33
	ds_write_b64 v68, v[66:67] offset:128
; template <bool LN1>
; __device__ __forceinline__ void ln_phase(Frame& F, const bf16_t* Yin, const float* ga, const float* be, const float* modf, float* stats, bf16_t* ob16, float* of32) {
;     ...
; #pragma unroll
;             for (int k = 0; k < 8; ++k) { pg8::unpack8(nx[k], v[k][0], v[k][1]);
;                 float s = ((v[k][0][0] + v[k][0][1]) + (v[k][0][2] + v[k][0][3])) + ((v[k][1][0] + v[k][1][1]) + (v[k][1][2] + v[k][1][3]));
;                 float q = ((v[k][0][0] * v[k][0][0] + v[k][0][1] * v[k][0][1]) + (v[k][0][2] * v[k][0][2] + v[k][0][3] * v[k][0][3])) + ((v[k][1][0] * v[k][1][0] + v[k][1][1] * v[k][1][1]) + (v[k][1][2] * v[k][1][2] + v[k][1][3] * v[k][1][3]));
;                 s = wave_sum(s); q = wave_sum(q);
;                 if (lane == 0) rd[k * 8 + w] = (f32x2){s, q}; }
.LBB0_1112:
	s_or_b64 exec, exec, s[0:1]
	v_lshlrev_b32_e32 v138, 16, v14
	v_and_b32_e32 v140, 0xffff0000, v14
	v_lshlrev_b32_e32 v142, 16, v15
	v_and_b32_e32 v144, 0xffff0000, v15
	v_lshlrev_b32_e32 v130, 16, v16
	v_and_b32_e32 v132, 0xffff0000, v16
	v_lshlrev_b32_e32 v134, 16, v17
	v_and_b32_e32 v136, 0xffff0000, v17
	v_mul_f32_e32 v139, v138, v138
	v_mul_f32_e32 v141, v140, v140
	v_mul_f32_e32 v143, v142, v142
	v_mul_f32_e32 v145, v144, v144
	v_mul_f32_e32 v131, v130, v130
	v_mul_f32_e32 v133, v132, v132
	v_mul_f32_e32 v135, v134, v134
	v_mul_f32_e32 v137, v136, v136
	v_pk_add_f32 v[66:67], v[138:139], v[140:141]
	s_waitcnt lgkmcnt(0)
	v_pk_add_f32 v[68:69], v[142:143], v[144:145]
	v_pk_add_f32 v[70:71], v[134:135], v[136:137]
	v_pk_add_f32 v[66:67], v[66:67], v[68:69]
	v_pk_add_f32 v[68:69], v[130:131], v[132:133]
	s_nop 0
	v_pk_add_f32 v[68:69], v[68:69], v[70:71]
	s_nop 0
	v_pk_add_f32 v[66:67], v[66:67], v[68:69]
	ds_bpermute_b32 v68, v1, v66
	ds_bpermute_b32 v69, v1, v67
	s_waitcnt lgkmcnt(0)
	v_pk_add_f32 v[66:67], v[66:67], v[68:69]
	ds_bpermute_b32 v68, v187, v66
	ds_bpermute_b32 v69, v187, v67
	s_waitcnt lgkmcnt(0)
	v_pk_add_f32 v[66:67], v[66:67], v[68:69]
	ds_bpermute_b32 v68, v200, v66
	ds_bpermute_b32 v69, v200, v67
	s_waitcnt lgkmcnt(0)
	v_pk_add_f32 v[66:67], v[66:67], v[68:69]
	ds_bpermute_b32 v68, v201, v66
	ds_bpermute_b32 v69, v201, v67
	s_waitcnt lgkmcnt(0)
	v_pk_add_f32 v[66:67], v[66:67], v[68:69]
	ds_bpermute_b32 v68, v202, v66
	ds_bpermute_b32 v69, v202, v67
	s_waitcnt lgkmcnt(0)
	v_pk_add_f32 v[66:67], v[66:67], v[68:69]
	ds_bpermute_b32 v68, v203, v66
	ds_bpermute_b32 v69, v203, v67
	s_and_saveexec_b64 s[0:1], s[2:3]
	s_cbranch_execz .LBB0_1114
	s_waitcnt lgkmcnt(0)
	v_pk_add_f32 v[66:67], v[66:67], v[68:69]
	v_mov_b32_e32 v68, s33
	ds_write_b64 v68, v[66:67] offset:192
.LBB0_1114:
	s_or_b64 exec, exec, s[0:1]
	v_lshlrev_b32_e32 v122, 16, v18
	v_and_b32_e32 v124, 0xffff0000, v18
	v_lshlrev_b32_e32 v126, 16, v19
	v_and_b32_e32 v128, 0xffff0000, v19
	v_lshlrev_b32_e32 v114, 16, v20
	v_and_b32_e32 v116, 0xffff0000, v20
	v_lshlrev_b32_e32 v118, 16, v21
	v_and_b32_e32 v120, 0xffff0000, v21
	v_mul_f32_e32 v123, v122, v122
	v_mul_f32_e32 v125, v124, v124
	v_mul_f32_e32 v127, v126, v126
	v_mul_f32_e32 v129, v128, v128
	v_mul_f32_e32 v115, v114, v114
	v_mul_f32_e32 v117, v116, v116
	v_mul_f32_e32 v119, v118, v118
	v_mul_f32_e32 v121, v120, v120
	v_pk_add_f32 v[66:67], v[122:123], v[124:125]
	s_waitcnt lgkmcnt(0)
	v_pk_add_f32 v[68:69], v[126:127], v[128:129]
	v_pk_add_f32 v[70:71], v[118:119], v[120:121]
	v_pk_add_f32 v[66:67], v[66:67], v[68:69]
	v_pk_add_f32 v[68:69], v[114:115], v[116:117]
	s_nop 0
	v_pk_add_f32 v[68:69], v[68:69], v[70:71]
	s_nop 0
	v_pk_add_f32 v[66:67], v[66:67], v[68:69]
	ds_bpermute_b32 v68, v1, v66
	ds_bpermute_b32 v69, v1, v67
	s_waitcnt lgkmcnt(0)
	v_pk_add_f32 v[66:67], v[66:67], v[68:69]
	ds_bpermute_b32 v68, v187, v66
	ds_bpermute_b32 v69, v187, v67
	s_waitcnt lgkmcnt(0)
	v_pk_add_f32 v[66:67], v[66:67], v[68:69]
	ds_bpermute_b32 v68, v200, v66
	ds_bpermute_b32 v69, v200, v67
	s_waitcnt lgkmcnt(0)
	v_pk_add_f32 v[66:67], v[66:67], v[68:69]
	ds_bpermute_b32 v68, v201, v66
	ds_bpermute_b32 v69, v201, v67
	s_waitcnt lgkmcnt(0)
	v_pk_add_f32 v[66:67], v[66:67], v[68:69]
	ds_bpermute_b32 v68, v202, v66
	ds_bpermute_b32 v69, v202, v67
	s_waitcnt lgkmcnt(0)
	v_pk_add_f32 v[66:67], v[66:67], v[68:69]
	ds_bpermute_b32 v68, v203, v66
	ds_bpermute_b32 v69, v203, v67
	s_and_saveexec_b64 s[0:1], s[2:3]
	s_cbranch_execz .LBB0_1116
	s_waitcnt lgkmcnt(0)
	v_pk_add_f32 v[66:67], v[66:67], v[68:69]
	v_mov_b32_e32 v68, s33
	ds_write_b64 v68, v[66:67] offset:256
.LBB0_1116:
	s_or_b64 exec, exec, s[0:1]
	v_lshlrev_b32_e32 v106, 16, v22
	v_and_b32_e32 v108, 0xffff0000, v22
	v_lshlrev_b32_e32 v110, 16, v23
	v_and_b32_e32 v112, 0xffff0000, v23
	v_lshlrev_b32_e32 v98, 16, v24
	v_and_b32_e32 v100, 0xffff0000, v24
	v_lshlrev_b32_e32 v102, 16, v25
	v_and_b32_e32 v104, 0xffff0000, v25
	v_mul_f32_e32 v107, v106, v106
	v_mul_f32_e32 v109, v108, v108
	v_mul_f32_e32 v111, v110, v110
	v_mul_f32_e32 v113, v112, v112
	v_mul_f32_e32 v99, v98, v98
	v_mul_f32_e32 v101, v100, v100
	v_mul_f32_e32 v103, v102, v102
	v_mul_f32_e32 v105, v104, v104
	v_pk_add_f32 v[66:67], v[106:107], v[108:109]
	s_waitcnt lgkmcnt(0)
	v_pk_add_f32 v[68:69], v[110:111], v[112:113]
	v_pk_add_f32 v[70:71], v[102:103], v[104:105]
	v_pk_add_f32 v[66:67], v[66:67], v[68:69]
	v_pk_add_f32 v[68:69], v[98:99], v[100:101]
	s_nop 0
	v_pk_add_f32 v[68:69], v[68:69], v[70:71]
	s_nop 0
	v_pk_add_f32 v[66:67], v[66:67], v[68:69]
	ds_bpermute_b32 v68, v1, v66
	ds_bpermute_b32 v69, v1, v67
	s_waitcnt lgkmcnt(0)
	v_pk_add_f32 v[66:67], v[66:67], v[68:69]
	ds_bpermute_b32 v68, v187, v66
	ds_bpermute_b32 v69, v187, v67
	s_waitcnt lgkmcnt(0)
	v_pk_add_f32 v[66:67], v[66:67], v[68:69]
	ds_bpermute_b32 v68, v200, v66
	ds_bpermute_b32 v69, v200, v67
	s_waitcnt lgkmcnt(0)
	v_pk_add_f32 v[66:67], v[66:67], v[68:69]
	ds_bpermute_b32 v68, v201, v66
	ds_bpermute_b32 v69, v201, v67
	s_waitcnt lgkmcnt(0)
	v_pk_add_f32 v[66:67], v[66:67], v[68:69]
	ds_bpermute_b32 v68, v202, v66
	ds_bpermute_b32 v69, v202, v67
	s_waitcnt lgkmcnt(0)
	v_pk_add_f32 v[66:67], v[66:67], v[68:69]
	ds_bpermute_b32 v68, v203, v66
	ds_bpermute_b32 v69, v203, v67
	s_and_saveexec_b64 s[0:1], s[2:3]
	s_cbranch_execz .LBB0_1118
	s_waitcnt lgkmcnt(0)
	v_pk_add_f32 v[66:67], v[66:67], v[68:69]
	v_mov_b32_e32 v68, s33
	ds_write_b64 v68, v[66:67] offset:320
; template <bool LN1>
; __device__ __forceinline__ void ln_phase(Frame& F, const bf16_t* Yin, const float* ga, const float* be, const float* modf, float* stats, bf16_t* ob16, float* of32) {
;     ...
; #pragma unroll
;             for (int k = 0; k < 8; ++k) { pg8::unpack8(nx[k], v[k][0], v[k][1]);
;                 float s = ((v[k][0][0] + v[k][0][1]) + (v[k][0][2] + v[k][0][3])) + ((v[k][1][0] + v[k][1][1]) + (v[k][1][2] + v[k][1][3]));
;                 float q = ((v[k][0][0] * v[k][0][0] + v[k][0][1] * v[k][0][1]) + (v[k][0][2] * v[k][0][2] + v[k][0][3] * v[k][0][3])) + ((v[k][1][0] * v[k][1][0] + v[k][1][1] * v[k][1][1]) + (v[k][1][2] * v[k][1][2] + v[k][1][3] * v[k][1][3]));
;                 s = wave_sum(s); q = wave_sum(q);
;                 if (lane == 0) rd[k * 8 + w] = (f32x2){s, q}; }
.LBB0_1118:
	s_or_b64 exec, exec, s[0:1]
	v_lshlrev_b32_e32 v90, 16, v26
	v_and_b32_e32 v92, 0xffff0000, v26
	v_lshlrev_b32_e32 v94, 16, v27
	v_and_b32_e32 v96, 0xffff0000, v27
	v_lshlrev_b32_e32 v82, 16, v28
	v_and_b32_e32 v84, 0xffff0000, v28
	v_lshlrev_b32_e32 v86, 16, v29
	v_and_b32_e32 v88, 0xffff0000, v29
	v_mul_f32_e32 v91, v90, v90
	v_mul_f32_e32 v93, v92, v92
	v_mul_f32_e32 v95, v94, v94
	v_mul_f32_e32 v97, v96, v96
	v_mul_f32_e32 v83, v82, v82
	v_mul_f32_e32 v85, v84, v84
	v_mul_f32_e32 v87, v86, v86
	v_mul_f32_e32 v89, v88, v88
	v_pk_add_f32 v[66:67], v[90:91], v[92:93]
	s_waitcnt lgkmcnt(0)
	v_pk_add_f32 v[68:69], v[94:95], v[96:97]
	v_pk_add_f32 v[70:71], v[86:87], v[88:89]
	v_pk_add_f32 v[66:67], v[66:67], v[68:69]
	v_pk_add_f32 v[68:69], v[82:83], v[84:85]
	s_nop 0
	v_pk_add_f32 v[68:69], v[68:69], v[70:71]
	s_nop 0
	v_pk_add_f32 v[66:67], v[66:67], v[68:69]
	ds_bpermute_b32 v68, v1, v66
	ds_bpermute_b32 v69, v1, v67
	s_waitcnt lgkmcnt(0)
	v_pk_add_f32 v[66:67], v[66:67], v[68:69]
	ds_bpermute_b32 v68, v187, v66
	ds_bpermute_b32 v69, v187, v67
	s_waitcnt lgkmcnt(0)
	v_pk_add_f32 v[66:67], v[66:67], v[68:69]
	ds_bpermute_b32 v68, v200, v66
	ds_bpermute_b32 v69, v200, v67
	s_waitcnt lgkmcnt(0)
	v_pk_add_f32 v[66:67], v[66:67], v[68:69]
	ds_bpermute_b32 v68, v201, v66
	ds_bpermute_b32 v69, v201, v67
	s_waitcnt lgkmcnt(0)
	v_pk_add_f32 v[66:67], v[66:67], v[68:69]
	ds_bpermute_b32 v68, v202, v66
	ds_bpermute_b32 v69, v202, v67
	s_waitcnt lgkmcnt(0)
	v_pk_add_f32 v[66:67], v[66:67], v[68:69]
	ds_bpermute_b32 v68, v203, v66
	ds_bpermute_b32 v69, v203, v67
	s_and_saveexec_b64 s[0:1], s[2:3]
	s_cbranch_execz .LBB0_1120
	s_waitcnt lgkmcnt(0)
	v_pk_add_f32 v[66:67], v[66:67], v[68:69]
	v_mov_b32_e32 v68, s33
	ds_write_b64 v68, v[66:67] offset:384
.LBB0_1120:
	s_or_b64 exec, exec, s[0:1]
	v_lshlrev_b32_e32 v74, 16, v30
	v_and_b32_e32 v76, 0xffff0000, v30
	v_lshlrev_b32_e32 v78, 16, v31
	v_and_b32_e32 v80, 0xffff0000, v31
	v_lshlrev_b32_e32 v66, 16, v32
	s_waitcnt lgkmcnt(1)
	v_and_b32_e32 v68, 0xffff0000, v32
	v_lshlrev_b32_e32 v70, 16, v33
	v_and_b32_e32 v72, 0xffff0000, v33
	v_mul_f32_e32 v75, v74, v74
	v_mul_f32_e32 v77, v76, v76
	v_mul_f32_e32 v79, v78, v78
	v_mul_f32_e32 v81, v80, v80
	v_mul_f32_e32 v67, v66, v66
	s_waitcnt lgkmcnt(0)
	v_mul_f32_e32 v69, v68, v68
	v_mul_f32_e32 v71, v70, v70
	v_mul_f32_e32 v73, v72, v72
	v_pk_add_f32 v[196:197], v[74:75], v[76:77]
	v_pk_add_f32 v[198:199], v[78:79], v[80:81]
	v_pk_add_f32 v[206:207], v[70:71], v[72:73]
	v_pk_add_f32 v[196:197], v[196:197], v[198:199]
	v_pk_add_f32 v[198:199], v[66:67], v[68:69]
	s_nop 0
	v_pk_add_f32 v[198:199], v[198:199], v[206:207]
	s_nop 0
	v_pk_add_f32 v[196:197], v[196:197], v[198:199]
	ds_bpermute_b32 v198, v1, v196
	ds_bpermute_b32 v199, v1, v197
	s_waitcnt lgkmcnt(0)
	v_pk_add_f32 v[196:197], v[196:197], v[198:199]
	ds_bpermute_b32 v198, v187, v196
	ds_bpermute_b32 v199, v187, v197
	s_waitcnt lgkmcnt(0)
	v_pk_add_f32 v[196:197], v[196:197], v[198:199]
	ds_bpermute_b32 v198, v200, v196
	ds_bpermute_b32 v199, v200, v197
	s_waitcnt lgkmcnt(0)
	v_pk_add_f32 v[196:197], v[196:197], v[198:199]
	ds_bpermute_b32 v198, v201, v196
	ds_bpermute_b32 v199, v201, v197
	s_waitcnt lgkmcnt(0)
	v_pk_add_f32 v[196:197], v[196:197], v[198:199]
	ds_bpermute_b32 v198, v202, v196
	ds_bpermute_b32 v199, v202, v197
	s_waitcnt lgkmcnt(0)
	v_pk_add_f32 v[196:197], v[196:197], v[198:199]
	ds_bpermute_b32 v198, v203, v196
	ds_bpermute_b32 v199, v203, v197
	s_and_saveexec_b64 s[0:1], s[2:3]
	s_cbranch_execz .LBB0_1122
	s_waitcnt lgkmcnt(0)
	v_pk_add_f32 v[196:197], v[196:197], v[198:199]
	v_mov_b32_e32 v67, s33
	ds_write_b64 v67, v[196:197] offset:448
; __device__ __forceinline__ size_t ytile(int row, int col) { return ((((size_t)(row >> 8) * 16) + (col >> 8)) * 256 + (row & 255)) * 256 + (col & 255); }
; template <bool LN1>
; __device__ __forceinline__ void ln_phase(Frame& F, const bf16_t* Yin, const float* ga, const float* be, const float* modf, float* stats, bf16_t* ob16, float* of32) {
;     ...
;             if (bt < 7) {
; #pragma unroll
;                 for (int k = 0; k < 8; ++k) nx[k] = *(const u32x4*)(Yin + ytile(r0 + 8 + k, c0));
;             }
;             __syncthreads();
; #pragma unroll
;             for (int k = 0; k < 8; ++k) {
;                 float s = 0.f, q = 0.f;
; #pragma unroll
;                 for (int ww = 0; ww < 8; ++ww) { const f32x2 p = rd[k * 8 + ww]; s += p[0]; q += p[1]; }
;                 const float mean = s * (1.0f / D), var = fmaxf(q * (1.0f / D) - mean * mean, 0.f), rstd = 1.0f / sqrtf(var + 1e-5f);
.LBB0_1122:
	s_or_b64 exec, exec, s[0:1]
	s_cmpk_lg_i32 s18, 0x1c0
	s_cbranch_scc0 .LBB0_1124
	s_waitcnt vmcnt(0)
	v_mov_b64_e32 v[2:3], v[218:219]
	v_mov_b64_e32 v[4:5], v[220:221]
	v_mov_b64_e32 v[6:7], v[222:223]
	v_mov_b64_e32 v[8:9], v[224:225]
	v_mov_b64_e32 v[10:11], v[226:227]
	v_mov_b64_e32 v[12:13], v[228:229]
	v_mov_b64_e32 v[14:15], v[230:231]
	v_mov_b64_e32 v[16:17], v[232:233]
	v_mov_b64_e32 v[18:19], v[234:235]
	v_mov_b64_e32 v[20:21], v[236:237]
	v_mov_b64_e32 v[22:23], v[238:239]
	v_mov_b64_e32 v[24:25], v[240:241]
	v_mov_b64_e32 v[26:27], v[246:247]
	v_mov_b64_e32 v[28:29], v[248:249]
	v_mov_b64_e32 v[30:31], v[250:251]
	v_mov_b64_e32 v[32:33], v[252:253]
	s_cmpk_gt_i32 s18, 0x140
	s_cbranch_scc1 .Lp6_nopf
	s_add_i32 s33, s28, 12
	s_ashr_i32 s0, s33, 8
	s_ashr_i32 s1, s0, 31
	s_lshl_b64 s[0:1], s[0:1], 12
	v_lshl_add_u64 v[242:243], s[0:1], 0, v[40:41]
	s_and_b32 s0, s33, 0xf8
	v_or_b32_e32 v254, s0, v242
	v_mov_b32_e32 v255, v243
	v_lshlrev_b64 v[254:255], 9, v[254:255]
	v_lshl_add_u64 v[254:255], v[42:43], 0, v[254:255]
	global_load_dwordx4 v[218:221], v[254:255], off
	v_or3_b32 v254, s0, 1, v242
	v_mov_b32_e32 v255, v243
	v_lshlrev_b64 v[254:255], 9, v[254:255]
	v_lshl_add_u64 v[254:255], v[42:43], 0, v[254:255]
	global_load_dwordx4 v[222:225], v[254:255], off
	v_or3_b32 v254, s0, 2, v242
	v_mov_b32_e32 v255, v243
	v_lshlrev_b64 v[254:255], 9, v[254:255]
	v_lshl_add_u64 v[254:255], v[42:43], 0, v[254:255]
	global_load_dwordx4 v[226:229], v[254:255], off
	v_or3_b32 v254, s0, 3, v242
	v_mov_b32_e32 v255, v243
	v_lshlrev_b64 v[254:255], 9, v[254:255]
	v_lshl_add_u64 v[254:255], v[42:43], 0, v[254:255]
	global_load_dwordx4 v[230:233], v[254:255], off
	v_or3_b32 v254, s0, 4, v242
	v_mov_b32_e32 v255, v243
	v_lshlrev_b64 v[254:255], 9, v[254:255]
	v_lshl_add_u64 v[254:255], v[42:43], 0, v[254:255]
	global_load_dwordx4 v[234:237], v[254:255], off
	v_or3_b32 v254, s0, 5, v242
	v_mov_b32_e32 v255, v243
	v_lshlrev_b64 v[254:255], 9, v[254:255]
	v_lshl_add_u64 v[254:255], v[42:43], 0, v[254:255]
	global_load_dwordx4 v[238:241], v[254:255], off
	v_or3_b32 v254, s0, 6, v242
	v_mov_b32_e32 v255, v243
	v_lshlrev_b64 v[254:255], 9, v[254:255]
	v_lshl_add_u64 v[254:255], v[42:43], 0, v[254:255]
	global_load_dwordx4 v[246:249], v[254:255], off
	v_or3_b32 v254, s0, 7, v242
	v_mov_b32_e32 v255, v243
	v_lshlrev_b64 v[254:255], 9, v[254:255]
	v_lshl_add_u64 v[254:255], v[42:43], 0, v[254:255]
	global_load_dwordx4 v[250:253], v[254:255], off
.Lp6_nopf:
.LBB0_1124:
	v_mov_b32_e32 v67, s29
	s_waitcnt lgkmcnt(0)
	s_barrier
	ds_read_b128 v[196:199], v67
	ds_read_b128 v[206:209], v67 offset:16
	ds_read_b128 v[210:213], v67 offset:32
	ds_read_b128 v[214:217], v67 offset:48
	s_waitcnt lgkmcnt(3)
	v_add_f32_e32 v67, 0, v196
	v_add_f32_e32 v67, v67, v198
	v_add_f32_e32 v69, 0, v197
	s_waitcnt lgkmcnt(2)
	v_add_f32_e32 v67, v67, v206
	v_add_f32_e32 v69, v69, v199
	v_add_f32_e32 v67, v67, v208
	v_add_f32_e32 v69, v69, v207
	s_waitcnt lgkmcnt(1)
	v_add_f32_e32 v67, v67, v210
	v_add_f32_e32 v69, v69, v209
	v_add_f32_e32 v67, v67, v212
	v_add_f32_e32 v69, v69, v211
	s_waitcnt lgkmcnt(0)
	v_add_f32_e32 v67, v67, v214
	v_add_f32_e32 v69, v69, v213
	v_add_f32_e32 v67, v67, v216
	v_add_f32_e32 v69, v69, v215
	v_mul_f32_e32 v196, 0x39800000, v67
	v_add_f32_e32 v69, v69, v217
	v_mul_f32_e32 v67, v196, v196
	v_fma_f32 v67, v69, s26, -v67
	v_max_f32_e32 v67, 0, v67
	v_add_f32_e32 v67, 0x3727c5ac, v67
	v_mul_f32_e32 v69, 0x4f800000, v67
	v_cmp_gt_f32_e32 vcc, s27, v67
	s_nop 1
	v_cndmask_b32_e32 v67, v67, v69, vcc
	v_sqrt_f32_e32 v69, v67
	s_nop 0
	v_add_u32_e32 v71, -1, v69
	v_fma_f32 v73, -v71, v69, v67
	v_cmp_ge_f32_e64 s[0:1], 0, v73
	v_add_u32_e32 v73, 1, v69
	s_nop 0
	v_cndmask_b32_e64 v71, v69, v71, s[0:1]
	v_fma_f32 v69, -v73, v69, v67
	v_cmp_lt_f32_e64 s[0:1], 0, v69
	s_nop 1
	v_cndmask_b32_e64 v69, v71, v73, s[0:1]
	v_mul_f32_e32 v71, 0x37800000, v69
	v_cndmask_b32_e32 v69, v69, v71, vcc
	v_cmp_class_f32_e32 vcc, v67, v204
	s_nop 1
	v_cndmask_b32_e32 v67, v69, v67, vcc
	v_div_scale_f32 v69, s[0:1], v67, v67, 1.0
	v_rcp_f32_e32 v71, v69
	s_nop 0
	v_fma_f32 v73, -v69, v71, 1.0
	v_fmac_f32_e32 v71, v73, v71
	v_div_scale_f32 v73, vcc, 1.0, v67, 1.0
	v_mul_f32_e32 v75, v73, v71
	v_fma_f32 v77, -v69, v75, v73
	v_fmac_f32_e32 v75, v77, v71
	v_fma_f32 v69, -v69, v75, v73
	v_div_fmas_f32 v69, v69, v71, v75
	v_div_fixup_f32 v198, v69, v67, 1.0
	s_and_saveexec_b64 s[0:1], s[8:9]
	s_cbranch_execz .LBB0_1126
	s_add_u32 s34, s7, s18
	s_addc_u32 s35, s22, s19
	v_mov_b32_e32 v197, v198
	global_store_dwordx2 v205, v[196:197], s[34:35]
